# P1 rstd-table fill: per-iteration row-partials loads go through LDS-DMA into per-wave staging slots, reduce and rsq after the loop (one exposed latency instead of one per iteration)
# baseline (speedup 1.0000x reference)
; #define LAS __attribute__((address_space(3)))
; __device__ __forceinline__ int otid() { int t = threadIdx.x; asm volatile("" : "+v"(t)); return t; }
; __device__ __forceinline__ float sum16(const float* p) { const f32x4 a = *(const f32x4*)p, b = *(const f32x4*)(p + 4), c = *(const f32x4*)(p + 8), d = *(const f32x4*)(p + 12); const f32x4 t = (a + b) + (c + d); return (t[0] + t[1]) + (t[2] + t[3]); }
;     __host__ __device__ bool next(int i, Unit& u) const { return at((long)i * G + c, u); }
;     __device__ bool next(int i, Unit& u) const { const long L = (long)i * G + c; if (L < 1280) return s0.at(L, u); if (!s1.at(L - 1280, u)) return false; u.kind = 1; return true; }
; template <class Sched> __device__ __forceinline__ void fill_rstd(LAS float* rl, const float* rowss, const Sched& S, int by_col  ) {
;     const int tid = otid();
;     for (int e = tid; e < 12 * 256; e += NTHREADS) { pg8::Unit u; const int i = e >> 8;
;         if (S.next(i, u)) { const bool bc = by_col < 0 ? (u.kind != 0) : (by_col != 0); const int r = (bc ? u.pn : u.pm) * 256 + (e & 255); rl[e] = rsqrtf(sum16(rowss + (size_t)r * 16) * (1.0f / 1024.0f) + EPS); } }
.LBB0_261:
	s_mov_b64 s[0:1], 0
	s_mov_b64 s[4:5], 0
	s_mov_b64 s[6:7], 0
	s_mov_b64 s[40:41], 0
	v_mov_b32_e32 v0, v232
	s_mov_b32 s93, s59
	s_nop 0
	v_mov_b32_e32 v87, 0
	s_mov_b32 s98, 0
	v_cmp_gt_i32_e32 vcc, s24, v0
	s_and_saveexec_b64 s[28:29], vcc
	s_cbranch_execz .LBB0_272
	s_add_u32 s16, s30, s40
	s_addc_u32 s17, s31, s41
	s_lshl_b64 s[10:11], s[92:93], 20
	s_add_u32 s10, s16, s10
	s_addc_u32 s11, s17, s11
	s_add_u32 s40, s10, 0x40000
	v_readlane_b32 s10, v255, 2
	s_addc_u32 s41, s11, 0
	v_and_b32_e32 v4, 0xff, v0
	v_lshl_add_u32 v5, v0, 2, s10
	v_mov_b32_e32 v86, v5
	s_mov_b64 s[42:43], 0
	s_branch .LBB0_264
.LBB0_263:
	s_add_i32 s98, s98, 1
	s_or_b64 exec, exec, s[68:69]
	v_add_u32_e32 v2, 0x200, v0
	v_cmp_lt_i32_e32 vcc, s85, v0
	v_add_u32_e32 v5, 0x800, v5
	s_or_b64 s[42:43], vcc, s[42:43]
	v_mov_b32_e32 v0, v2
	s_andn2_b64 exec, exec, s[42:43]
	s_cbranch_execz .LBB0_272

; __device__ __forceinline__ float sum16(const float* p) { const f32x4 a = *(const f32x4*)p, b = *(const f32x4*)(p + 4), c = *(const f32x4*)(p + 8), d = *(const f32x4*)(p + 12); const f32x4 t = (a + b) + (c + d); return (t[0] + t[1]) + (t[2] + t[3]); }
;     __device__ bool next(int i, Unit& u) const { const long L = (long)i * G + c; if (L < 1280) return s0.at(L, u); if (!s1.at(L - 1280, u)) return false; u.kind = 1; return true; }
;     __host__ __device__ bool next(int i, Unit& u) const { return at((long)i * G + c, u); }
;     __host__ __device__ bool at(long L, Unit& u) const {
;         if (L >= nwg) return false;
;         u.kind = 0;
;         int wgid = (int)L; { const int q = nwg / NXCD, r = nwg % NXCD, xcd = wgid % NXCD, off = wgid / NXCD; wgid = (xcd < r ? xcd * (q + 1) : r * (q + 1) + (xcd - r) * q) + off; }
;         const int nig = WGM * nN, gid = wgid / nig, fm = gid * WGM, gsz = (nM - fm) < WGM ? (nM - fm) : WGM;
;         u.pm = fm + ((wgid % nig) % gsz); u.pn = (wgid % nig) / gsz; return true;
;     }
; template <class Sched> __device__ __forceinline__ void fill_rstd(LAS float* rl, const float* rowss, const Sched& S, int by_col  ) {
;     ...
;     for (int e = tid; e < 12 * 256; e += NTHREADS) { pg8::Unit u; const int i = e >> 8;
;         if (S.next(i, u)) { const bool bc = by_col < 0 ? (u.kind != 0) : (by_col != 0); const int r = (bc ? u.pn : u.pm) * 256 + (e & 255); rl[e] = rsqrtf(sum16(rowss + (size_t)r * 16) * (1.0f / 1024.0f) + EPS); } }
.LBB0_270:
	v_ashrrev_i32_e32 v3, 31, v2
	v_lshrrev_b32_e32 v3, 29, v3
	v_add_u32_e32 v3, v2, v3
	v_ashrrev_i32_e32 v6, 3, v3
	v_and_b32_e32 v3, -8, v3
	v_sub_u32_e32 v2, v2, v3
	v_cmp_gt_i32_e32 vcc, 0, v2
	v_mov_b32_e32 v3, 0xa0
	v_mov_b32_e32 v7, 0xa1
	v_cndmask_b32_e32 v3, v3, v7, vcc
	v_mul_lo_u32 v2, v2, v3
	v_add_u32_e32 v2, v2, v6
	s_mov_b32 s10, 0x66666667
	v_mul_hi_i32 v3, v2, s10
	v_lshrrev_b32_e32 v6, 31, v3
	v_ashrrev_i32_e32 v3, 6, v3
	v_add_u32_e32 v3, v3, v6
	v_lshlrev_b32_e32 v8, 3, v3
	v_sub_u32_e32 v6, 64, v8
	v_min_i32_e32 v9, 8, v6
	v_sub_u32_e32 v6, 0, v9
	v_max_i32_e32 v7, v9, v6
	v_cvt_f32_u32_e32 v10, v7
	s_movk_i32 s10, 0xa0
	v_mul_lo_u32 v3, v3, s10
	v_sub_u32_e32 v12, 0, v7
	v_rcp_iflag_f32_e32 v10, v10
	v_sub_u32_e32 v2, v2, v3
	v_sub_u32_e32 v11, 0, v2
	v_max_i32_e32 v11, v2, v11
	v_mul_f32_e32 v10, 0x4f7ffffe, v10
	v_cvt_u32_f32_e32 v10, v10
	v_xor_b32_e32 v3, v2, v9
	v_ashrrev_i32_e32 v3, 31, v3
	v_mov_b32_e32 v6, 0
	v_mul_lo_u32 v12, v12, v10
	v_mul_hi_u32 v12, v10, v12
	v_add_u32_e32 v10, v10, v12
	v_mul_hi_u32 v10, v11, v10
	v_mul_lo_u32 v12, v10, v7
	v_sub_u32_e32 v11, v11, v12
	v_add_u32_e32 v12, 1, v10
	v_cmp_ge_u32_e32 vcc, v11, v7
	s_or_b64 s[44:45], s[44:45], exec
	s_nop 0
	v_cndmask_b32_e32 v10, v10, v12, vcc
	v_sub_u32_e32 v12, v11, v7
	v_cndmask_b32_e32 v11, v11, v12, vcc
	v_add_u32_e32 v12, 1, v10
	v_cmp_ge_u32_e32 vcc, v11, v7
	s_nop 1
	v_cndmask_b32_e32 v7, v10, v12, vcc
	v_xor_b32_e32 v7, v7, v3
	v_sub_u32_e32 v7, v7, v3
	v_mul_lo_u32 v3, v7, v9
	v_sub_u32_e32 v2, v2, v3
	v_add_u32_e32 v8, v8, v2
	s_or_b64 exec, exec, s[68:69]
	s_and_saveexec_b64 s[68:69], s[44:45]
	s_cbranch_execz .LBB0_263
.LBB0_271:
	v_cmp_eq_u32_e32 vcc, 0, v6
	s_nop 1
	v_cndmask_b32_e32 v2, v7, v8, vcc
	v_lshl_or_b32 v2, v2, 8, v4
	v_ashrrev_i32_e32 v3, 31, v2
	v_lshlrev_b64 v[2:3], 6, v[2:3]
	v_lshl_add_u64 v[2:3], s[40:41], 0, v[2:3]
	s_mov_b64 s[100:101], exec
	s_cmp_eq_u32 s98, 0
	s_cbranch_scc0 .Lmy_fr_m1
	v_writelane_b32 v87, s100, 0
	v_writelane_b32 v87, s101, 1
.Lmy_fr_m1:
	s_cmp_eq_u32 s98, 1
	s_cbranch_scc0 .Lmy_fr_m2
	v_writelane_b32 v87, s100, 2
	v_writelane_b32 v87, s101, 3
.Lmy_fr_m2:
	s_cmp_eq_u32 s98, 2
	s_cbranch_scc0 .Lmy_fr_m3
	v_writelane_b32 v87, s100, 4
	v_writelane_b32 v87, s101, 5
.Lmy_fr_m3:
	s_cmp_eq_u32 s98, 3
	s_cbranch_scc0 .Lmy_fr_m4
	v_writelane_b32 v87, s100, 6
	v_writelane_b32 v87, s101, 7
.Lmy_fr_m4:
	v_readfirstlane_b32 s100, v232
	s_min_u32 s99, s98, 3
	s_lshr_b32 s100, s100, 6
	s_lshl_b32 s99, s99, 12
	s_lshl_b32 s100, s100, 14
	s_add_i32 s99, s99, s100
	s_mov_b32 m0, s99
	v_lshl_add_u64 v[88:89], v[2:3], 0, 16
	global_load_lds_dwordx4 v[2:3], off
	s_add_i32 m0, s99, 0x400
	v_lshl_add_u64 v[90:91], v[2:3], 0, 32
	global_load_lds_dwordx4 v[88:89], off
	s_add_i32 m0, s99, 0x800
	v_lshl_add_u64 v[88:89], v[2:3], 0, 48
	global_load_lds_dwordx4 v[90:91], off
	s_add_i32 m0, s99, 0xc00
	s_nop 0
	global_load_lds_dwordx4 v[88:89], off
	s_branch .LBB0_263
.LBB0_272:
	s_or_b64 exec, exec, s[28:29]
	s_waitcnt vmcnt(0)
	v_lshrrev_b32_e32 v88, 6, v232
	v_and_b32_e32 v89, 63, v232
	v_lshlrev_b32_e32 v88, 14, v88
	v_lshl_or_b32 v88, v89, 4, v88
	v_readlane_b32 s100, v87, 0
	v_readlane_b32 s101, v87, 1
	s_nop 3
	s_mov_b64 exec, s[100:101]
	s_cbranch_execz .Lmy_fr_c0
	ds_read_b128 v[10:13], v88 offset:0
	ds_read_b128 v[14:17], v88 offset:1024
	ds_read_b128 v[18:21], v88 offset:2048
	ds_read_b128 v[22:25], v88 offset:3072
	v_add_u32_e32 v90, 0, v86
	s_waitcnt lgkmcnt(0)
	v_pk_add_f32 v[2:3], v[12:13], v[16:17]
	v_pk_add_f32 v[10:11], v[10:11], v[14:15]
	v_pk_add_f32 v[12:13], v[20:21], v[24:25]
	v_pk_add_f32 v[14:15], v[18:19], v[22:23]
	v_pk_add_f32 v[2:3], v[2:3], v[12:13]
	v_pk_add_f32 v[10:11], v[10:11], v[14:15]
	s_nop 0
	v_pk_mov_b32 v[12:13], v[10:11], v[2:3] op_sel:[1,0]
	v_mov_b32_e32 v11, v3
	v_pk_add_f32 v[2:3], v[12:13], v[10:11]
	s_nop 0
	v_add_f32_e32 v2, v2, v3
	v_fmamk_f32 v2, v2, 0x3a800000, v234
	v_mul_f32_e32 v3, 0x4b800000, v2
	v_cmp_gt_f32_e32 vcc, s65, v2
	s_nop 1
	v_cndmask_b32_e32 v2, v2, v3, vcc
	v_rsq_f32_e32 v2, v2
	s_nop 0
	v_mul_f32_e32 v3, 0x45800000, v2
	v_cndmask_b32_e32 v2, v2, v3, vcc
	ds_write_b32 v90, v2
; __device__ __forceinline__ float sum16(const float* p) { const f32x4 a = *(const f32x4*)p, b = *(const f32x4*)(p + 4), c = *(const f32x4*)(p + 8), d = *(const f32x4*)(p + 12); const f32x4 t = (a + b) + (c + d); return (t[0] + t[1]) + (t[2] + t[3]); }
;     __host__ __device__ bool next(int i, Unit& u) const { return at((long)i * G + c, u); }
;     __device__ bool next(int i, Unit& u) const { const long L = (long)i * G + c; if (L < 1280) return s0.at(L, u); if (!s1.at(L - 1280, u)) return false; u.kind = 1; return true; }
; template <class Sched> __device__ __forceinline__ void fill_rstd(LAS float* rl, const float* rowss, const Sched& S, int by_col  ) {
;     ...
;     for (int e = tid; e < 12 * 256; e += NTHREADS) { pg8::Unit u; const int i = e >> 8;
;         if (S.next(i, u)) { const bool bc = by_col < 0 ? (u.kind != 0) : (by_col != 0); const int r = (bc ? u.pn : u.pm) * 256 + (e & 255); rl[e] = rsqrtf(sum16(rowss + (size_t)r * 16) * (1.0f / 1024.0f) + EPS); } }
;     __syncthreads();
.Lmy_fr_c0:
	v_readlane_b32 s100, v87, 2
	v_readlane_b32 s101, v87, 3
	s_nop 3
	s_mov_b64 exec, s[100:101]
	s_cbranch_execz .Lmy_fr_c1
	ds_read_b128 v[10:13], v88 offset:4096
	ds_read_b128 v[14:17], v88 offset:5120
	ds_read_b128 v[18:21], v88 offset:6144
	ds_read_b128 v[22:25], v88 offset:7168
	v_add_u32_e32 v90, 2048, v86
	s_waitcnt lgkmcnt(0)
	v_pk_add_f32 v[2:3], v[12:13], v[16:17]
	v_pk_add_f32 v[10:11], v[10:11], v[14:15]
	v_pk_add_f32 v[12:13], v[20:21], v[24:25]
	v_pk_add_f32 v[14:15], v[18:19], v[22:23]
	v_pk_add_f32 v[2:3], v[2:3], v[12:13]
	v_pk_add_f32 v[10:11], v[10:11], v[14:15]
	s_nop 0
	v_pk_mov_b32 v[12:13], v[10:11], v[2:3] op_sel:[1,0]
	v_mov_b32_e32 v11, v3
	v_pk_add_f32 v[2:3], v[12:13], v[10:11]
	s_nop 0
	v_add_f32_e32 v2, v2, v3
	v_fmamk_f32 v2, v2, 0x3a800000, v234
	v_mul_f32_e32 v3, 0x4b800000, v2
	v_cmp_gt_f32_e32 vcc, s65, v2
	s_nop 1
	v_cndmask_b32_e32 v2, v2, v3, vcc
	v_rsq_f32_e32 v2, v2
	s_nop 0
	v_mul_f32_e32 v3, 0x45800000, v2
	v_cndmask_b32_e32 v2, v2, v3, vcc
	ds_write_b32 v90, v2
.Lmy_fr_c1:
	v_readlane_b32 s100, v87, 4
	v_readlane_b32 s101, v87, 5
	s_nop 3
	s_mov_b64 exec, s[100:101]
	s_cbranch_execz .Lmy_fr_c2
	ds_read_b128 v[10:13], v88 offset:8192
	ds_read_b128 v[14:17], v88 offset:9216
	ds_read_b128 v[18:21], v88 offset:10240
	ds_read_b128 v[22:25], v88 offset:11264
	v_add_u32_e32 v90, 4096, v86
	s_waitcnt lgkmcnt(0)
	v_pk_add_f32 v[2:3], v[12:13], v[16:17]
	v_pk_add_f32 v[10:11], v[10:11], v[14:15]
	v_pk_add_f32 v[12:13], v[20:21], v[24:25]
	v_pk_add_f32 v[14:15], v[18:19], v[22:23]
	v_pk_add_f32 v[2:3], v[2:3], v[12:13]
	v_pk_add_f32 v[10:11], v[10:11], v[14:15]
	s_nop 0
	v_pk_mov_b32 v[12:13], v[10:11], v[2:3] op_sel:[1,0]
	v_mov_b32_e32 v11, v3
	v_pk_add_f32 v[2:3], v[12:13], v[10:11]
	s_nop 0
	v_add_f32_e32 v2, v2, v3
	v_fmamk_f32 v2, v2, 0x3a800000, v234
	v_mul_f32_e32 v3, 0x4b800000, v2
	v_cmp_gt_f32_e32 vcc, s65, v2
	s_nop 1
	v_cndmask_b32_e32 v2, v2, v3, vcc
	v_rsq_f32_e32 v2, v2
	s_nop 0
	v_mul_f32_e32 v3, 0x45800000, v2
	v_cndmask_b32_e32 v2, v2, v3, vcc
	ds_write_b32 v90, v2
.Lmy_fr_c2:
	v_readlane_b32 s100, v87, 6
	v_readlane_b32 s101, v87, 7
	s_nop 3
	s_mov_b64 exec, s[100:101]
	s_cbranch_execz .Lmy_fr_c3
	ds_read_b128 v[10:13], v88 offset:12288
	ds_read_b128 v[14:17], v88 offset:13312
	ds_read_b128 v[18:21], v88 offset:14336
	ds_read_b128 v[22:25], v88 offset:15360
	v_add_u32_e32 v90, 6144, v86
	s_waitcnt lgkmcnt(0)
	v_pk_add_f32 v[2:3], v[12:13], v[16:17]
	v_pk_add_f32 v[10:11], v[10:11], v[14:15]
	v_pk_add_f32 v[12:13], v[20:21], v[24:25]
	v_pk_add_f32 v[14:15], v[18:19], v[22:23]
	v_pk_add_f32 v[2:3], v[2:3], v[12:13]
	v_pk_add_f32 v[10:11], v[10:11], v[14:15]
	s_nop 0
	v_pk_mov_b32 v[12:13], v[10:11], v[2:3] op_sel:[1,0]
	v_mov_b32_e32 v11, v3
	v_pk_add_f32 v[2:3], v[12:13], v[10:11]
	s_nop 0
	v_add_f32_e32 v2, v2, v3
	v_fmamk_f32 v2, v2, 0x3a800000, v234
	v_mul_f32_e32 v3, 0x4b800000, v2
	v_cmp_gt_f32_e32 vcc, s65, v2
	s_nop 1
	v_cndmask_b32_e32 v2, v2, v3, vcc
	v_rsq_f32_e32 v2, v2
	s_nop 0
	v_mul_f32_e32 v3, 0x45800000, v2
	v_cndmask_b32_e32 v2, v2, v3, vcc
	ds_write_b32 v90, v2
.Lmy_fr_c3:
	s_mov_b64 exec, s[28:29]
	s_add_u32 s10, s30, s0
	s_addc_u32 s11, s31, s1
	s_lshl_b64 s[0:1], s[92:93], 25
	s_add_u32 s0, s10, s0
	s_addc_u32 s1, s11, s1
	s_add_u32 s0, s0, 0xa240000
	s_addc_u32 s1, s1, 0
	v_readlane_b32 s10, v255, 41
	s_add_u32 s4, s10, s4
	s_addc_u32 s5, s80, s5
	s_add_u32 s4, s4, 0x1440000
	s_addc_u32 s5, s5, 0
	s_add_u32 s6, s10, s6
	s_addc_u32 s7, s80, s7
	s_add_u32 s6, s6, 0x1e40000
	s_mov_b64 s[40:41], 0
	s_mov_b64 s[42:43], 0
	s_waitcnt vmcnt(1)
	v_mov_b32_e32 v16, v232
	s_addc_u32 s7, s7, 0
	s_waitcnt lgkmcnt(0)
	s_barrier
	s_andn2_b64 vcc, exec, s[48:49]
	v_readfirstlane_b32 s25, v16
	s_cbranch_vccnz .LBB0_274
	v_readlane_b32 s11, v254, 37
	s_mov_b32 s94, s11
	v_readlane_b32 s11, v254, 38
	v_readlane_b32 s68, v254, 35
	s_mov_b32 s10, 1
	s_mov_b32 s84, s11
	s_mov_b64 s[28:29], s[0:1]
	s_mov_b64 s[44:45], s[6:7]
	v_readlane_b32 s69, v254, 36
	s_andn2_b64 vcc, exec, s[68:69]
	s_cbranch_vccz .LBB0_275
	s_branch .LBB0_293
